# v21 + down-GEMM epilogue: the second residual batch's cache lines touched (8 one-dword loads) while the first batch is in flight
# baseline (speedup 1.0000x reference)
.LBB0_1417:
	s_mov_b64 s[46:47], 0x40000
	v_lshl_or_b32 v146, s61, 8, v216
	v_lshl_add_u32 v144, s62, 8, v214
	s_lshl_b64 s[4:5], s[4:5], 2
	v_ashrrev_i32_e32 v147, 31, v146
	s_add_u32 s4, s11, s4
	v_lshlrev_b64 v[192:193], 1, v[146:147]
	v_ashrrev_i32_e32 v145, 31, v144
	s_addc_u32 s5, s13, s5
	v_lshl_add_u64 v[194:195], s[80:81], 0, v[192:193]
	v_lshlrev_b64 v[196:197], 11, v[144:145]
	v_lshl_add_u64 v[124:125], v[146:147], 2, s[4:5]
	v_lshl_add_u64 v[146:147], v[194:195], 0, v[196:197]
	global_load_dwordx4 v[128:131], v[124:125], off offset:16
	global_load_dwordx4 v[132:135], v[124:125], off
	global_load_dwordx4 v[120:123], v[124:125], off offset:528
	s_nop 0
	global_load_dwordx4 v[124:127], v[124:125], off offset:512
	s_nop 0
	v_lshl_add_u64 v[224:225], v[146:147], 0, s[46:47]
	global_load_dwordx4 v[218:221], v[146:147], off
	global_load_dwordx4 v[168:171], v[146:147], off offset:256
	global_load_dword v223, v[224:225], off
	global_load_dword v223, v[224:225], off offset:256
	v_or_b32_e32 v146, 16, v144
	v_ashrrev_i32_e32 v147, 31, v146
	v_lshlrev_b64 v[202:203], 11, v[146:147]
	v_lshl_add_u64 v[146:147], v[194:195], 0, v[202:203]
	v_lshl_add_u64 v[226:227], v[146:147], 0, s[46:47]
	global_load_dwordx4 v[164:167], v[146:147], off
	global_load_dwordx4 v[160:163], v[146:147], off offset:256
	global_load_dword v223, v[226:227], off
	global_load_dword v223, v[226:227], off offset:256
	v_or_b32_e32 v146, 32, v144
	v_ashrrev_i32_e32 v147, 31, v146
	v_lshlrev_b64 v[200:201], 11, v[146:147]
	v_lshl_add_u64 v[146:147], v[194:195], 0, v[200:201]
	v_lshl_add_u64 v[228:229], v[146:147], 0, s[46:47]
	global_load_dwordx4 v[156:159], v[146:147], off
	global_load_dwordx4 v[148:151], v[146:147], off offset:256
	global_load_dword v223, v[228:229], off
	global_load_dword v223, v[228:229], off offset:256
	v_or_b32_e32 v144, 48, v144
	v_ashrrev_i32_e32 v145, 31, v144
	v_lshlrev_b64 v[198:199], 11, v[144:145]
	v_lshl_add_u64 v[144:145], v[194:195], 0, v[198:199]
	v_lshl_add_u64 v[230:231], v[144:145], 0, s[46:47]
	global_load_dwordx4 v[152:155], v[144:145], off
	s_nop 0
	global_load_dwordx4 v[144:147], v[144:145], off offset:256
	global_load_dword v223, v[230:231], off
	global_load_dword v223, v[230:231], off offset:256
	s_mov_b64 s[4:5], 0x40000
	s_and_b64 vcc, exec, s[42:43]
	s_waitcnt vmcnt(0)
	v_lshlrev_b32_e32 v222, 16, v218
	v_fmac_f32_e32 v222, v140, v132
	v_and_b32_e32 v140, 0xffff0000, v218
	v_fmac_f32_e32 v140, v141, v133
	v_lshlrev_b32_e32 v141, 16, v219
	v_fmac_f32_e32 v141, v142, v134
	v_and_b32_e32 v142, 0xffff0000, v219
	v_fmac_f32_e32 v142, v143, v135
	v_cvt_pk_bf16_f32 v140, v222, v140
	v_cvt_pk_bf16_f32 v141, v141, v142
	v_lshlrev_b32_e32 v142, 16, v220
	v_fmac_f32_e32 v142, v136, v128
	v_and_b32_e32 v136, 0xffff0000, v220
	v_fmac_f32_e32 v136, v137, v129
	v_cvt_pk_bf16_f32 v142, v142, v136
	v_lshlrev_b32_e32 v136, 16, v221
	v_fmac_f32_e32 v136, v138, v130
	v_lshlrev_b32_e32 v138, 16, v168
	v_and_b32_e32 v137, 0xffff0000, v221
	v_fmac_f32_e32 v138, v116, v124
	v_and_b32_e32 v116, 0xffff0000, v168
	v_fmac_f32_e32 v137, v139, v131
	v_fmac_f32_e32 v116, v117, v125
	v_lshlrev_b32_e32 v117, 16, v169
	v_cvt_pk_bf16_f32 v143, v136, v137
	v_lshl_add_u64 v[136:137], s[28:29], 0, v[196:197]
	v_fmac_f32_e32 v117, v118, v126
	v_and_b32_e32 v118, 0xffff0000, v169
	v_lshl_add_u64 v[136:137], v[136:137], 0, v[192:193]
	v_fmac_f32_e32 v118, v119, v127
	global_store_dwordx4 v[136:137], v[140:143], off
	v_cvt_pk_bf16_f32 v116, v138, v116
	v_cvt_pk_bf16_f32 v117, v117, v118
	v_lshlrev_b32_e32 v118, 16, v170
	v_fmac_f32_e32 v118, v112, v120
	v_and_b32_e32 v112, 0xffff0000, v170
	v_fmac_f32_e32 v112, v113, v121
	v_cvt_pk_bf16_f32 v118, v118, v112
	v_lshlrev_b32_e32 v112, 16, v171
	v_fmac_f32_e32 v112, v114, v122
	v_and_b32_e32 v113, 0xffff0000, v171
	v_fmac_f32_e32 v113, v115, v123
	v_cvt_pk_bf16_f32 v119, v112, v113
	v_lshlrev_b32_e32 v112, 16, v164
	v_fmac_f32_e32 v112, v108, v132
	v_and_b32_e32 v108, 0xffff0000, v164
	v_fmac_f32_e32 v108, v109, v133
	v_lshlrev_b32_e32 v109, 16, v165
	v_fmac_f32_e32 v109, v110, v134
	v_and_b32_e32 v110, 0xffff0000, v165
	v_fmac_f32_e32 v110, v111, v135
	global_store_dwordx4 v[136:137], v[116:119], off offset:256
	v_cvt_pk_bf16_f32 v108, v112, v108
	v_cvt_pk_bf16_f32 v109, v109, v110
	v_lshlrev_b32_e32 v110, 16, v166
	v_fmac_f32_e32 v110, v104, v128
	v_and_b32_e32 v104, 0xffff0000, v166
	v_fmac_f32_e32 v104, v105, v129
	v_cvt_pk_bf16_f32 v110, v110, v104
	v_lshlrev_b32_e32 v104, 16, v167
	v_fmac_f32_e32 v104, v106, v130
	v_lshlrev_b32_e32 v106, 16, v160
	v_and_b32_e32 v105, 0xffff0000, v167
	v_fmac_f32_e32 v106, v100, v124
	v_and_b32_e32 v100, 0xffff0000, v160
	v_fmac_f32_e32 v105, v107, v131
	v_fmac_f32_e32 v100, v101, v125
	v_lshlrev_b32_e32 v101, 16, v161
	v_cvt_pk_bf16_f32 v111, v104, v105
	v_lshl_add_u64 v[104:105], s[28:29], 0, v[202:203]
	v_fmac_f32_e32 v101, v102, v126
	v_and_b32_e32 v102, 0xffff0000, v161
	v_lshl_add_u64 v[104:105], v[104:105], 0, v[192:193]
	v_fmac_f32_e32 v102, v103, v127
	global_store_dwordx4 v[104:105], v[108:111], off
	v_cvt_pk_bf16_f32 v100, v106, v100
	v_cvt_pk_bf16_f32 v101, v101, v102
	v_lshlrev_b32_e32 v102, 16, v162
	v_fmac_f32_e32 v102, v92, v120
	v_and_b32_e32 v92, 0xffff0000, v162
	v_fmac_f32_e32 v92, v93, v121
	v_cvt_pk_bf16_f32 v102, v102, v92
	v_lshlrev_b32_e32 v92, 16, v163
	v_and_b32_e32 v93, 0xffff0000, v163
	v_fmac_f32_e32 v92, v94, v122
	v_fmac_f32_e32 v93, v95, v123
	v_cvt_pk_bf16_f32 v103, v92, v93
	v_lshlrev_b32_e32 v92, 16, v156
	v_and_b32_e32 v93, 0xffff0000, v156
	v_fmac_f32_e32 v92, v96, v132
	v_fmac_f32_e32 v93, v97, v133
	global_store_dwordx4 v[104:105], v[100:103], off offset:256
	v_cvt_pk_bf16_f32 v92, v92, v93
	v_lshlrev_b32_e32 v93, 16, v157
	v_and_b32_e32 v94, 0xffff0000, v157
	v_fmac_f32_e32 v93, v98, v134
	v_fmac_f32_e32 v94, v99, v135
	v_cvt_pk_bf16_f32 v93, v93, v94
	v_lshlrev_b32_e32 v94, 16, v158
	v_fmac_f32_e32 v94, v88, v128
	v_and_b32_e32 v88, 0xffff0000, v158
	v_fmac_f32_e32 v88, v89, v129
	v_cvt_pk_bf16_f32 v94, v94, v88
	v_lshlrev_b32_e32 v88, 16, v159
	v_fmac_f32_e32 v88, v90, v130
	v_lshlrev_b32_e32 v90, 16, v148
	v_and_b32_e32 v89, 0xffff0000, v159
	v_fmac_f32_e32 v90, v84, v124
	v_and_b32_e32 v84, 0xffff0000, v148
	v_fmac_f32_e32 v89, v91, v131
	v_fmac_f32_e32 v84, v85, v125
	v_lshlrev_b32_e32 v85, 16, v149
	v_cvt_pk_bf16_f32 v95, v88, v89
	v_lshl_add_u64 v[88:89], s[28:29], 0, v[200:201]
	v_fmac_f32_e32 v85, v86, v126
	v_and_b32_e32 v86, 0xffff0000, v149
	v_lshl_add_u64 v[88:89], v[88:89], 0, v[192:193]
	v_fmac_f32_e32 v86, v87, v127
	global_store_dwordx4 v[88:89], v[92:95], off
	v_cvt_pk_bf16_f32 v84, v90, v84
	v_cvt_pk_bf16_f32 v85, v85, v86
	v_lshlrev_b32_e32 v86, 16, v150
	v_fmac_f32_e32 v86, v76, v120
	v_and_b32_e32 v76, 0xffff0000, v150
	v_fmac_f32_e32 v76, v77, v121
	v_cvt_pk_bf16_f32 v86, v86, v76
	v_lshlrev_b32_e32 v76, 16, v151
	v_and_b32_e32 v77, 0xffff0000, v151
	v_fmac_f32_e32 v76, v78, v122
	v_fmac_f32_e32 v77, v79, v123
	v_cvt_pk_bf16_f32 v87, v76, v77
	v_lshlrev_b32_e32 v76, 16, v152
	v_and_b32_e32 v77, 0xffff0000, v152
	v_fmac_f32_e32 v76, v80, v132
	v_fmac_f32_e32 v77, v81, v133
	global_store_dwordx4 v[88:89], v[84:87], off offset:256
	v_cvt_pk_bf16_f32 v76, v76, v77
	v_lshlrev_b32_e32 v77, 16, v153
	v_and_b32_e32 v78, 0xffff0000, v153
	v_fmac_f32_e32 v77, v82, v134
	v_fmac_f32_e32 v78, v83, v135
	v_cvt_pk_bf16_f32 v77, v77, v78
	v_lshlrev_b32_e32 v78, 16, v154
	v_fmac_f32_e32 v78, v72, v128
	v_and_b32_e32 v72, 0xffff0000, v154
	v_fmac_f32_e32 v72, v73, v129
	v_cvt_pk_bf16_f32 v78, v78, v72
	v_lshlrev_b32_e32 v72, 16, v155
	v_fmac_f32_e32 v72, v74, v130
	v_lshlrev_b32_e32 v74, 16, v144
	v_and_b32_e32 v73, 0xffff0000, v155
	v_fmac_f32_e32 v74, v68, v124
	v_and_b32_e32 v68, 0xffff0000, v144
	v_fmac_f32_e32 v73, v75, v131
	v_fmac_f32_e32 v68, v69, v125
	v_lshlrev_b32_e32 v69, 16, v145
	v_cvt_pk_bf16_f32 v79, v72, v73
	v_lshl_add_u64 v[72:73], s[28:29], 0, v[198:199]
	v_fmac_f32_e32 v69, v70, v126
	v_and_b32_e32 v70, 0xffff0000, v145
	v_lshl_add_u64 v[72:73], v[72:73], 0, v[192:193]
	v_fmac_f32_e32 v70, v71, v127
	global_store_dwordx4 v[72:73], v[76:79], off
	v_cvt_pk_bf16_f32 v68, v74, v68
	v_cvt_pk_bf16_f32 v69, v69, v70
	v_lshlrev_b32_e32 v70, 16, v146
	v_fmac_f32_e32 v70, v64, v120
	v_and_b32_e32 v64, 0xffff0000, v146
	v_fmac_f32_e32 v64, v65, v121
	v_cvt_pk_bf16_f32 v70, v70, v64
	v_lshlrev_b32_e32 v64, 16, v147
	v_and_b32_e32 v65, 0xffff0000, v147
	v_fmac_f32_e32 v64, v66, v122
	v_fmac_f32_e32 v65, v67, v123
	v_lshl_add_u64 v[96:97], v[196:197], 0, s[4:5]
	v_cvt_pk_bf16_f32 v71, v64, v65
	global_store_dwordx4 v[72:73], v[68:71], off offset:256
	v_lshl_add_u64 v[64:65], v[194:195], 0, v[96:97]
	global_load_dwordx4 v[68:71], v[64:65], off
	global_load_dwordx4 v[72:75], v[64:65], off offset:256
	s_mov_b64 s[4:5], 0x48000
	v_lshl_add_u64 v[98:99], v[196:197], 0, s[4:5]
	v_lshl_add_u64 v[64:65], v[194:195], 0, v[98:99]
	global_load_dwordx4 v[76:79], v[64:65], off
	global_load_dwordx4 v[80:83], v[64:65], off offset:256
	s_mov_b64 s[4:5], 0x50000
	v_lshl_add_u64 v[100:101], v[196:197], 0, s[4:5]
	v_lshl_add_u64 v[64:65], v[194:195], 0, v[100:101]
	global_load_dwordx4 v[84:87], v[64:65], off
	global_load_dwordx4 v[88:91], v[64:65], off offset:256
	s_mov_b64 s[4:5], 0x58000
	v_lshl_add_u64 v[102:103], v[196:197], 0, s[4:5]
	v_lshl_add_u64 v[64:65], v[194:195], 0, v[102:103]
	global_load_dwordx4 v[92:95], v[64:65], off
	s_nop 0
	global_load_dwordx4 v[64:67], v[64:65], off offset:256
	s_mov_b64 s[4:5], -1
	s_waitcnt vmcnt(7)
	v_lshlrev_b32_e32 v104, 16, v68
	v_fmac_f32_e32 v104, v60, v132
	v_and_b32_e32 v60, 0xffff0000, v68
	v_fmac_f32_e32 v60, v61, v133
	v_lshlrev_b32_e32 v61, 16, v69
	v_fmac_f32_e32 v61, v62, v134
	v_and_b32_e32 v62, 0xffff0000, v69
	v_fmac_f32_e32 v62, v63, v135
	v_cvt_pk_bf16_f32 v60, v104, v60
	v_cvt_pk_bf16_f32 v61, v61, v62
	v_lshlrev_b32_e32 v62, 16, v70
	v_fmac_f32_e32 v62, v56, v128
	v_and_b32_e32 v56, 0xffff0000, v70
	v_fmac_f32_e32 v56, v57, v129
	v_cvt_pk_bf16_f32 v62, v62, v56
	v_lshlrev_b32_e32 v56, 16, v71
	v_fmac_f32_e32 v56, v58, v130
	s_waitcnt vmcnt(6)
	v_lshlrev_b32_e32 v58, 16, v72
	v_and_b32_e32 v57, 0xffff0000, v71
	v_fmac_f32_e32 v58, v52, v124
	v_and_b32_e32 v52, 0xffff0000, v72
	v_fmac_f32_e32 v57, v59, v131
	v_fmac_f32_e32 v52, v53, v125
	v_lshlrev_b32_e32 v53, 16, v73
	v_cvt_pk_bf16_f32 v63, v56, v57
	v_lshl_add_u64 v[56:57], s[28:29], 0, v[96:97]
	v_fmac_f32_e32 v53, v54, v126
	v_and_b32_e32 v54, 0xffff0000, v73
	v_lshl_add_u64 v[56:57], v[56:57], 0, v[192:193]
	v_fmac_f32_e32 v54, v55, v127
	global_store_dwordx4 v[56:57], v[60:63], off
	v_cvt_pk_bf16_f32 v52, v58, v52
	v_cvt_pk_bf16_f32 v53, v53, v54
	v_lshlrev_b32_e32 v54, 16, v74
	v_fmac_f32_e32 v54, v44, v120
	v_and_b32_e32 v44, 0xffff0000, v74
	v_fmac_f32_e32 v44, v45, v121
	v_cvt_pk_bf16_f32 v54, v54, v44
	v_lshlrev_b32_e32 v44, 16, v75
	v_and_b32_e32 v45, 0xffff0000, v75
	v_fmac_f32_e32 v44, v46, v122
	v_fmac_f32_e32 v45, v47, v123
	v_cvt_pk_bf16_f32 v55, v44, v45
	s_waitcnt vmcnt(6)
	v_lshlrev_b32_e32 v44, 16, v76
	v_and_b32_e32 v45, 0xffff0000, v76
	v_fmac_f32_e32 v44, v48, v132
	v_fmac_f32_e32 v45, v49, v133
	global_store_dwordx4 v[56:57], v[52:55], off offset:256
	v_cvt_pk_bf16_f32 v44, v44, v45
	v_lshlrev_b32_e32 v45, 16, v77
	v_and_b32_e32 v46, 0xffff0000, v77
	v_fmac_f32_e32 v45, v50, v134
	v_fmac_f32_e32 v46, v51, v135
	v_cvt_pk_bf16_f32 v45, v45, v46
	v_lshlrev_b32_e32 v46, 16, v78
	v_fmac_f32_e32 v46, v40, v128
	v_and_b32_e32 v40, 0xffff0000, v78
	v_fmac_f32_e32 v40, v41, v129
	v_cvt_pk_bf16_f32 v46, v46, v40
	v_lshlrev_b32_e32 v40, 16, v79
	v_fmac_f32_e32 v40, v42, v130
	s_waitcnt vmcnt(6)
	v_lshlrev_b32_e32 v42, 16, v80
	v_and_b32_e32 v41, 0xffff0000, v79
	v_fmac_f32_e32 v42, v36, v124
	v_and_b32_e32 v36, 0xffff0000, v80
	v_fmac_f32_e32 v41, v43, v131
	v_fmac_f32_e32 v36, v37, v125
	v_lshlrev_b32_e32 v37, 16, v81
	v_cvt_pk_bf16_f32 v47, v40, v41
	v_lshl_add_u64 v[40:41], s[28:29], 0, v[98:99]
	v_fmac_f32_e32 v37, v38, v126
	v_and_b32_e32 v38, 0xffff0000, v81
	v_lshl_add_u64 v[40:41], v[40:41], 0, v[192:193]
	v_fmac_f32_e32 v38, v39, v127
	global_store_dwordx4 v[40:41], v[44:47], off
	v_cvt_pk_bf16_f32 v36, v42, v36
	v_cvt_pk_bf16_f32 v37, v37, v38
	v_lshlrev_b32_e32 v38, 16, v82
	v_fmac_f32_e32 v38, v28, v120
	v_and_b32_e32 v28, 0xffff0000, v82
	v_fmac_f32_e32 v28, v29, v121
	v_cvt_pk_bf16_f32 v38, v38, v28
	v_lshlrev_b32_e32 v28, 16, v83
	v_and_b32_e32 v29, 0xffff0000, v83
	v_fmac_f32_e32 v28, v30, v122
	v_fmac_f32_e32 v29, v31, v123
	v_cvt_pk_bf16_f32 v39, v28, v29
	s_waitcnt vmcnt(6)
	v_lshlrev_b32_e32 v28, 16, v84
	v_and_b32_e32 v29, 0xffff0000, v84
	v_fmac_f32_e32 v28, v32, v132
	v_fmac_f32_e32 v29, v33, v133
	global_store_dwordx4 v[40:41], v[36:39], off offset:256
	v_cvt_pk_bf16_f32 v28, v28, v29
	v_lshlrev_b32_e32 v29, 16, v85
	v_and_b32_e32 v30, 0xffff0000, v85
	v_fmac_f32_e32 v29, v34, v134
	v_fmac_f32_e32 v30, v35, v135
	v_cvt_pk_bf16_f32 v29, v29, v30
	v_lshlrev_b32_e32 v30, 16, v86
	v_fmac_f32_e32 v30, v24, v128
	v_and_b32_e32 v24, 0xffff0000, v86
	v_fmac_f32_e32 v24, v25, v129
	v_cvt_pk_bf16_f32 v30, v30, v24
	v_lshlrev_b32_e32 v24, 16, v87
	v_fmac_f32_e32 v24, v26, v130
	s_waitcnt vmcnt(6)
	v_lshlrev_b32_e32 v26, 16, v88
	v_and_b32_e32 v25, 0xffff0000, v87
	v_fmac_f32_e32 v26, v20, v124
	v_and_b32_e32 v20, 0xffff0000, v88
	v_fmac_f32_e32 v25, v27, v131
	v_fmac_f32_e32 v20, v21, v125
	v_lshlrev_b32_e32 v21, 16, v89
	v_cvt_pk_bf16_f32 v31, v24, v25
	v_lshl_add_u64 v[24:25], s[28:29], 0, v[100:101]
	v_fmac_f32_e32 v21, v22, v126
	v_and_b32_e32 v22, 0xffff0000, v89
	v_lshl_add_u64 v[24:25], v[24:25], 0, v[192:193]
	v_fmac_f32_e32 v22, v23, v127
	global_store_dwordx4 v[24:25], v[28:31], off
	v_cvt_pk_bf16_f32 v20, v26, v20
	v_cvt_pk_bf16_f32 v21, v21, v22
	v_lshlrev_b32_e32 v22, 16, v90
	v_fmac_f32_e32 v22, v12, v120
	v_and_b32_e32 v12, 0xffff0000, v90
	v_fmac_f32_e32 v12, v13, v121
	v_cvt_pk_bf16_f32 v22, v22, v12
	v_lshlrev_b32_e32 v12, 16, v91
	v_and_b32_e32 v13, 0xffff0000, v91
	v_fmac_f32_e32 v12, v14, v122
	v_fmac_f32_e32 v13, v15, v123
	v_cvt_pk_bf16_f32 v23, v12, v13
	s_waitcnt vmcnt(6)
	v_lshlrev_b32_e32 v12, 16, v92
	v_and_b32_e32 v13, 0xffff0000, v92
	v_fmac_f32_e32 v12, v16, v132
	v_fmac_f32_e32 v13, v17, v133
	global_store_dwordx4 v[24:25], v[20:23], off offset:256
	v_cvt_pk_bf16_f32 v12, v12, v13
	v_lshlrev_b32_e32 v13, 16, v93
	v_and_b32_e32 v14, 0xffff0000, v93
	v_fmac_f32_e32 v13, v18, v134
	v_fmac_f32_e32 v14, v19, v135
	v_cvt_pk_bf16_f32 v13, v13, v14
	v_lshlrev_b32_e32 v14, 16, v94
	v_fmac_f32_e32 v14, v8, v128
	v_and_b32_e32 v8, 0xffff0000, v94
	v_fmac_f32_e32 v8, v9, v129
	v_cvt_pk_bf16_f32 v14, v14, v8
	v_lshlrev_b32_e32 v8, 16, v95
	v_fmac_f32_e32 v8, v10, v130
	s_waitcnt vmcnt(6)
	v_lshlrev_b32_e32 v10, 16, v64
	v_and_b32_e32 v9, 0xffff0000, v95
	v_fmac_f32_e32 v10, v4, v124
	v_and_b32_e32 v4, 0xffff0000, v64
	v_fmac_f32_e32 v9, v11, v131
	v_fmac_f32_e32 v4, v5, v125
	v_lshlrev_b32_e32 v5, 16, v65
	v_cvt_pk_bf16_f32 v15, v8, v9
	v_lshl_add_u64 v[8:9], s[28:29], 0, v[102:103]
	v_fmac_f32_e32 v5, v6, v126
	v_and_b32_e32 v6, 0xffff0000, v65
	v_lshl_add_u64 v[8:9], v[8:9], 0, v[192:193]
	v_fmac_f32_e32 v6, v7, v127
	global_store_dwordx4 v[8:9], v[12:15], off
	v_cvt_pk_bf16_f32 v4, v10, v4
	v_cvt_pk_bf16_f32 v5, v5, v6
	v_lshlrev_b32_e32 v6, 16, v66
	v_fmac_f32_e32 v6, v0, v120
	v_and_b32_e32 v0, 0xffff0000, v66
	v_fmac_f32_e32 v0, v1, v121
	v_cvt_pk_bf16_f32 v6, v6, v0
	v_lshlrev_b32_e32 v0, 16, v67
	v_and_b32_e32 v1, 0xffff0000, v67
	v_fmac_f32_e32 v0, v2, v122
	v_fmac_f32_e32 v1, v3, v123
	v_cvt_pk_bf16_f32 v7, v0, v1
	global_store_dwordx4 v[8:9], v[4:7], off offset:256
	s_cbranch_vccnz .LBB0_1404
	s_andn2_b64 vcc, exec, s[0:1]
	s_cbranch_vccnz .LBB0_1403
	s_barrier
	s_branch .LBB0_1403
